# in-proj GEMM epilogue (EpiStore): same per-wave LDS stash of the rstd factors, flag in LDS cleared at every phase start
# speedup vs baseline: 1.0049x; 1.0033x over previous
; #define LAS __attribute__((address_space(3)))
; __global__ void __launch_bounds__(NTHREADS, 2) trunk_fwd(Args a) {
;     ...
;         int tid = threadIdx.x; asm volatile("" : "+v"(tid));
;         unsigned tb_ = 131072 + 2048; asm volatile("" : "+s"(tb_));
;         volatile LAS unsigned long long* tab = (volatile LAS unsigned long long*)(lds + tb_);
;         unsigned char* ws = a.ws; asm volatile("" : "+s"(ws));
;         float* OUT = a.out; asm volatile("" : "+s"(OUT));
;         const int lane = tid & 63, wave = __builtin_amdgcn_readfirstlane(tid >> 6);
;         const int bid = blockIdx.x, G = gridDim.x, gw = bid * NWAVES + wave, ngw = G * NWAVES, gtid = bid * NTHREADS + tid, gthreads = G * NTHREADS;
;         bf16* H = (bf16*)(ws + WS_XN); bf16* MIX = (bf16*)OUT; float* SSA = (float*)(ws + WS_SS); float* SSB = SSA + (size_t)T * 32;
;         bf16* P = (bf16*)(ws + WS_P); bf16* ACT = P;
;         bf16* LO = (bf16*)(ws + WS_LO); bf16* QB = LO;
;         bf16* AL = (bf16*)(ws + WS_AL); bf16* KPE = AL;
;         bf16* SI = (bf16*)(ws + WS_SI); bf16* KVB = SI;
;         float* SW = (float*)(ws + WS_SW); bf16* PD = (bf16*)(ws + WS_SW); bf16* QN = PD + (size_t)T * 512; bf16* KVN = QN + (size_t)T * 512;
;         bf16* SV = (bf16*)(ws + WS_SV);
;         float* ROPE = (float*)(ws + WS_ROPE);
;         bf16* FGU = (bf16*)(ws + WS_FGU + (size_t)(L & 1) * SZ_FFN); bf16* FD = (bf16*)(ws + WS_FD + (size_t)(L & 1) * SZ_FFN);
;         LAS float* scr = (LAS float*)(lds + wave * 8448);
;         const int j = L >> 1;
;         int gsel = -1;
;         if (kind == 0 || kind == 2 || kind == 20 || kind == 22) gsel = 0;
;         else if (kind == 6 || kind == 9 || kind == 24 || kind == 27) gsel = 1;
;         else if (kind == 8 || kind == 26) gsel = 2;
;         if (kind == 100) {
;             for (int jj = 0; jj < 2; ++jj) {
;                 zero_lora_pool((bf16*)(ws + WS_EVLORA + jj * SZ_EVLORA), (bf16*)(ws + WS_POOL + jj * SZ_POOL), gtid, gthreads);
;                 zero_fill(ws + WS_EVIN + jj * SZ_EVIN + (size_t)EV_IN * D * 2, (size_t)(EV_IN_P - EV_IN) * D * 2, gtid, gthreads);
;                 zero_fill(ws + WS_ODIN + jj * SZ_ODIN + (size_t)OD_IN * D * 2, (size_t)(OD_IN_P - OD_IN) * D * 2, gtid, gthreads);
;             }
;             rope_table((const int*)INF(1), ROPE, gtid, gthreads);
;             init_rows(INF(0), H, SSB, gw, ngw, lane);
.LBB0_87:
	v_lshrrev_b32_e32 v186, 6, v216
	v_lshlrev_b32_e32 v186, 2, v186
	v_add_u32_e32 v186, 0x22000, v186
	v_mov_b32_e32 v185, 0
	ds_write_b32 v186, v185
	v_readlane_b32 s72, v252, 2
	v_readlane_b32 s86, v252, 16
	v_readlane_b32 s87, v252, 17
	v_mov_b32_e32 v186, v216
	s_mov_b32 s92, 0x20800
	s_mov_b64 s[88:89], s[90:91]
	s_mov_b64 s[0:1], s[86:87]
	v_readlane_b32 s77, v252, 7
	v_writelane_b32 v254, s0, 57
	v_and_b32_e32 v185, 63, v186
	s_mov_b64 s[4:5], -1
	v_writelane_b32 v254, s1, 58
	v_readfirstlane_b32 s0, v186
	s_ashr_i32 s52, s0, 6
	v_readlane_b32 s0, v253, 37
	s_add_i32 s10, s52, s0
	s_add_u32 s0, s88, 0xfa00000
	s_addc_u32 s1, s89, 0
	v_writelane_b32 v254, s0, 59
	s_mov_b64 s[22:23], 0
	v_readlane_b32 s73, v252, 3
	v_writelane_b32 v254, s1, 60
	s_add_u32 s0, s88, 0x35810000
	s_addc_u32 s1, s89, 0
	v_writelane_b32 v254, s0, 61
	v_readlane_b32 s74, v252, 4
	v_readlane_b32 s75, v252, 5
	v_writelane_b32 v254, s1, 62
	s_add_u32 s0, s88, 0x13a00000
	s_addc_u32 s1, s89, 0
	v_writelane_b32 v254, s0, 63
	v_readlane_b32 s76, v252, 6
	v_readlane_b32 s77, v254, 56
	v_writelane_b32 v255, s1, 0
	s_add_u32 s0, s88, 0x20a00000
	s_addc_u32 s1, s89, 0
	v_writelane_b32 v255, s0, 1
	v_readlane_b32 s78, v252, 8
	v_readlane_b32 s79, v252, 9
	v_writelane_b32 v255, s1, 2
	s_add_u32 s0, s88, 0x26a00000
	s_addc_u32 s1, s89, 0
	v_writelane_b32 v255, s0, 3
	v_readlane_b32 s80, v252, 10
	v_readlane_b32 s81, v252, 11
	v_writelane_b32 v255, s1, 4
	s_add_u32 s0, s88, 0x27600000
	s_addc_u32 s1, s89, 0
	v_writelane_b32 v255, s0, 5
	v_readlane_b32 s82, v252, 12
	v_readlane_b32 s83, v252, 13
	v_writelane_b32 v255, s1, 6
	s_add_u32 s0, s88, 0x2f600000
	s_addc_u32 s1, s89, 0
	v_writelane_b32 v255, s0, 7
	v_readlane_b32 s84, v252, 14
	v_readlane_b32 s85, v252, 15
	v_writelane_b32 v255, s1, 8
	s_add_u32 s0, s88, 0x30600000
	s_addc_u32 s1, s89, 0
	v_writelane_b32 v255, s0, 9
	s_nop 1
	v_writelane_b32 v255, s1, 10
	s_add_u32 s0, s88, 0x31600000
	s_addc_u32 s1, s89, 0
	v_writelane_b32 v255, s0, 11
	s_add_u32 s56, s88, 0xf600000
	s_addc_u32 s57, s89, 0
	v_writelane_b32 v255, s1, 12
	s_mul_i32 s0, s52, 0x2100
	s_add_i32 s43, s0, 0
	s_cmp_lt_i32 s77, 22
	s_cbranch_scc1 .LBB0_96
	s_cmp_gt_i32 s77, 29
	s_mov_b64 s[0:1], 0
	s_cbranch_scc0 .LBB0_220
	s_cmpk_lt_i32 s77, 0x64
	s_mov_b64 s[0:1], -1
	s_cbranch_scc1 .LBB0_214
	v_writelane_b32 v255, s52, 13
	s_cmpk_eq_i32 s77, 0x64
	s_cbranch_scc0 .LBB0_213
	v_readlane_b32 s0, v253, 38
	s_add_u32 s34, s88, 0x3400000
	s_addc_u32 s35, s89, 0
	s_waitcnt vmcnt(0)
	v_add_u32_e32 v0, s0, v186
	s_mov_b32 s0, 0x24000
	v_cmp_gt_i32_e32 vcc, s0, v0
	v_readlane_b32 s0, v254, 17
	s_nop 1
	v_lshl_add_u32 v2, v186, 3, s0
	s_and_saveexec_b64 s[0:1], vcc
	v_readlane_b32 s8, v253, 35
	s_mov_b32 s14, 0x54442d18
	v_readlane_b32 s62, v254, 36
	v_readlane_b32 s9, v253, 36
	s_mov_b32 s15, 0x401921fb
	v_readlane_b32 s11, v254, 18
	v_readlane_b32 s17, v254, 20
	s_mov_b32 s19, 0x2aaaaaab
	s_movk_i32 s28, 0xffd0
	s_movk_i32 s30, 0x400
	s_movk_i32 s31, 0xfe80
	s_mov_b32 s33, 0x23fff
	s_movk_i32 s46, 0x7fff
	s_mov_b32 s47, 0xfa00000
	s_movk_i32 s49, 0xf800
	s_movk_i32 s52, 0xf810
	v_readlane_b32 s63, v254, 37
	s_mov_b64 s[44:45], 0xdfff
	v_readlane_b32 s74, v255, 13
	s_cbranch_execz .LBB0_97
	v_readlane_b32 s2, v254, 17
	s_mov_b64 s[4:5], 0
	v_mov_b32_e32 v6, v0
	v_lshl_add_u32 v4, v186, 3, s2
	s_branch .LBB0_94

; __device__ __forceinline__ void tile_rstd(float (&rs)[2][4], const float* ssp, int rowtile, int wr, int fr, int fq) {
;     const int lane = fq * 16 + fr; f32x4 pa[2][4][2];
; #pragma unroll
;     for (int ai = 0; ai < 2; ++ai)
; #pragma unroll
;         for (int m = 0; m < 4; ++m) { const f32x4* p = (const f32x4*)(ssp + (size_t)(rowtile + wr * 64 + ai * HALF + m * 16 + (lane >> 2)) * 32 + (lane & 3) * 8); pa[ai][m][0] = p[0]; pa[ai][m][1] = p[1]; }
; #pragma unroll
;     for (int ai = 0; ai < 2; ++ai)
; #pragma unroll
;         for (int m = 0; m < 4; ++m) { const f32x4 a = pa[ai][m][0], b = pa[ai][m][1];
;             float t = ((a.x + a.y) + (a.z + a.w)) + ((b.x + b.y) + (b.z + b.w));
;             t += __shfl_xor(t, 1); t += __shfl_xor(t, 2);
;             rs[ai][m] = __shfl(rsqrtf(t * (1.0f / 2048.0f) + 1e-6f), fr * 4); }
;     __device__ __forceinline__ void operator()(const f32x4 (&acc)[2][2][4][2], const Unit& u, int wr, int wc, int fr, int fq) const {
;         const int row0 = u.pm * BM + wr * 64 + fr; const int col0 = u.pn * BM + wc * 32 + 8 * fq;
;         float rsa[2][4];
; #pragma unroll
;         for (int ai = 0; ai < 2; ++ai)
; #pragma unroll
;             for (int m = 0; m < 4; ++m) rsa[ai][m] = 1.0f;
;         if (ss) tile_rstd(rsa, ss, u.pm * BM, wr, fr, fq);
.LBB0_513:
	s_lshl_b32 s0, s52, 8
	s_andn2_b64 vcc, exec, s[84:85]
	s_add_i32 s0, s0, s6
	s_cbranch_vccnz .LBB0_515
	v_lshrrev_b32_e32 v131, 6, v216
	v_lshlrev_b32_e32 v131, 2, v131
	v_add_u32_e32 v131, 0x22000, v131
	ds_read_b32 v132, v131
	s_waitcnt lgkmcnt(0)
	v_readfirstlane_b32 vcc_lo, v132
	s_add_i32 vcc_lo, vcc_lo, -1
	s_cmp_eq_u32 vcc_lo, s52
	s_cbranch_scc1 .Lst_hit
	v_or_b32_e32 v130, s0, v204
	v_ashrrev_i32_e32 v131, 31, v130
	v_lshlrev_b64 v[132:133], 7, v[130:131]
	v_lshl_add_u64 v[132:133], v[184:185], 0, v[132:133]
	global_load_dwordx4 v[212:215], v[132:133], off
	global_load_dwordx4 v[232:235], v[132:133], off offset:16
	v_or_b32_e32 v132, 16, v130
	v_ashrrev_i32_e32 v133, 31, v132
	v_lshlrev_b64 v[132:133], 7, v[132:133]
	v_lshl_add_u64 v[132:133], v[184:185], 0, v[132:133]
	global_load_dwordx4 v[242:245], v[132:133], off
	global_load_dwordx4 v[246:249], v[132:133], off offset:16
	v_or_b32_e32 v132, 32, v130
	v_ashrrev_i32_e32 v133, 31, v132
	v_lshlrev_b64 v[132:133], 7, v[132:133]
	v_lshl_add_u64 v[132:133], v[184:185], 0, v[132:133]
	global_load_dwordx4 v[170:173], v[132:133], off
	global_load_dwordx4 v[174:177], v[132:133], off offset:16
	v_or_b32_e32 v132, 48, v130
	v_ashrrev_i32_e32 v133, 31, v132
	v_lshlrev_b64 v[132:133], 7, v[132:133]
	v_lshl_add_u64 v[132:133], v[184:185], 0, v[132:133]
	global_load_dwordx4 v[166:169], v[132:133], off
	global_load_dwordx4 v[162:165], v[132:133], off offset:16
	v_add_u32_e32 v132, 0x80, v130
	v_ashrrev_i32_e32 v133, 31, v132
	v_lshlrev_b64 v[132:133], 7, v[132:133]
	v_lshl_add_u64 v[132:133], v[184:185], 0, v[132:133]
	global_load_dwordx4 v[158:161], v[132:133], off
	global_load_dwordx4 v[154:157], v[132:133], off offset:16
	v_add_u32_e32 v132, 0x90, v130
	v_ashrrev_i32_e32 v133, 31, v132
	v_lshlrev_b64 v[132:133], 7, v[132:133]
	v_lshl_add_u64 v[132:133], v[184:185], 0, v[132:133]
	global_load_dwordx4 v[150:153], v[132:133], off
	global_load_dwordx4 v[146:149], v[132:133], off offset:16
	v_add_u32_e32 v132, 0xa0, v130
	v_ashrrev_i32_e32 v133, 31, v132
	v_lshlrev_b64 v[132:133], 7, v[132:133]
	v_add_u32_e32 v130, 0xb0, v130
	v_lshl_add_u64 v[132:133], v[184:185], 0, v[132:133]
	v_ashrrev_i32_e32 v131, 31, v130
	global_load_dwordx4 v[142:145], v[132:133], off
	global_load_dwordx4 v[138:141], v[132:133], off offset:16
	v_lshlrev_b64 v[130:131], 7, v[130:131]
	v_lshl_add_u64 v[130:131], v[184:185], 0, v[130:131]
	global_load_dwordx4 v[134:137], v[130:131], off
	s_nop 0
	global_load_dwordx4 v[130:133], v[130:131], off offset:16
	v_and_b32_e32 v192, 64, v220
	v_xor_b32_e32 v190, 1, v220
	v_add_u32_e32 v192, 64, v192
	v_cmp_lt_i32_e32 vcc, v190, v192
	s_waitcnt vmcnt(0) lgkmcnt(0)
	v_mov_b32_e32 v202, v212
	v_mov_b32_e32 v203, v232
	v_mov_b32_e32 v232, v213
	v_mov_b32_e32 v212, v214
	v_mov_b32_e32 v213, v234
	v_mov_b32_e32 v234, v215
	v_pk_add_f32 v[202:203], v[202:203], v[232:233]
	v_pk_add_f32 v[212:213], v[212:213], v[234:235]
	v_mov_b32_e32 v214, v244
	v_pk_add_f32 v[202:203], v[202:203], v[212:213]
	v_mov_b32_e32 v212, v242
	v_mov_b32_e32 v213, v246
	v_mov_b32_e32 v246, v243
	v_mov_b32_e32 v215, v248
	v_mov_b32_e32 v248, v245
	v_pk_add_f32 v[212:213], v[212:213], v[246:247]
	v_pk_add_f32 v[214:215], v[214:215], v[248:249]
	v_cndmask_b32_e32 v190, v220, v190, vcc
	v_pk_add_f32 v[212:213], v[212:213], v[214:215]
	v_mov_b32_e32 v215, v202
	v_mov_b32_e32 v214, v212
	v_mov_b32_e32 v202, v213
	v_lshlrev_b32_e32 v210, 2, v190
	v_pk_add_f32 v[202:203], v[214:215], v[202:203]
	ds_bpermute_b32 v213, v210, v203
	ds_bpermute_b32 v212, v210, v202
	v_xor_b32_e32 v190, 2, v220
	v_cmp_lt_i32_e32 vcc, v190, v192
	s_waitcnt lgkmcnt(0)
	v_pk_add_f32 v[202:203], v[202:203], v[212:213]
	v_cndmask_b32_e32 v190, v220, v190, vcc
	v_lshlrev_b32_e32 v209, 2, v190
	ds_bpermute_b32 v213, v209, v203
	ds_bpermute_b32 v212, v209, v202
	v_lshlrev_b32_e32 v190, 2, v220
	v_and_or_b32 v208, v190, s25, v205
	s_waitcnt lgkmcnt(0)
	v_pk_add_f32 v[212:213], v[202:203], v[212:213]
	v_mov_b64_e32 v[202:203], s[24:25]
	v_pk_fma_f32 v[212:213], v[212:213], s[18:19], v[202:203] op_sel_hi:[1,0,0]
	s_nop 0
	v_mul_f32_e32 v190, 0x4b800000, v213
	v_cmp_gt_f32_e64 s[40:41], s12, v213
	v_cmp_gt_f32_e32 vcc, s12, v212
	s_nop 0
	v_cndmask_b32_e64 v190, v213, v190, s[40:41]
	v_rsq_f32_e32 v190, v190
	v_mov_b32_e32 v213, v174
	v_mov_b32_e32 v174, v171
	v_mul_f32_e32 v192, 0x45800000, v190
	v_cndmask_b32_e64 v190, v190, v192, s[40:41]
	ds_bpermute_b32 v192, v208, v190
	v_mul_f32_e32 v190, 0x4b800000, v212
	v_cndmask_b32_e32 v190, v212, v190, vcc
	v_mov_b32_e32 v212, v170
	v_pk_add_f32 v[170:171], v[212:213], v[174:175]
	v_mov_b32_e32 v174, v172
	v_mov_b32_e32 v175, v176
	v_mov_b32_e32 v176, v173
	v_pk_add_f32 v[172:173], v[174:175], v[176:177]
	v_rsq_f32_e32 v190, v190
	v_pk_add_f32 v[170:171], v[170:171], v[172:173]
	v_mov_b32_e32 v172, v166
	v_mov_b32_e32 v173, v162
	v_mov_b32_e32 v162, v167
	v_mov_b32_e32 v166, v168
	v_mov_b32_e32 v167, v164
	v_mov_b32_e32 v164, v169
	v_pk_add_f32 v[162:163], v[172:173], v[162:163]
	v_pk_add_f32 v[164:165], v[166:167], v[164:165]
	v_mov_b32_e32 v166, v158
	v_pk_add_f32 v[162:163], v[162:163], v[164:165]
	v_mov_b32_e32 v165, v170
	v_mov_b32_e32 v164, v162
	v_mov_b32_e32 v170, v163
	v_pk_add_f32 v[162:163], v[164:165], v[170:171]
	ds_bpermute_b32 v165, v210, v163
	ds_bpermute_b32 v164, v210, v162
	v_mov_b32_e32 v167, v154
	v_mov_b32_e32 v154, v159
	v_mov_b32_e32 v158, v160
	v_mov_b32_e32 v159, v156
	v_mov_b32_e32 v156, v161
	v_pk_add_f32 v[154:155], v[166:167], v[154:155]
	v_pk_add_f32 v[156:157], v[158:159], v[156:157]
	s_waitcnt lgkmcnt(0)
; __device__ __forceinline__ void tile_rstd(float (&rs)[2][4], const float* ssp, int rowtile, int wr, int fr, int fq) {
;     ...
;         for (int m = 0; m < 4; ++m) { const f32x4 a = pa[ai][m][0], b = pa[ai][m][1];
;             float t = ((a.x + a.y) + (a.z + a.w)) + ((b.x + b.y) + (b.z + b.w));
;             t += __shfl_xor(t, 1); t += __shfl_xor(t, 2);
;             rs[ai][m] = __shfl(rsqrtf(t * (1.0f / 2048.0f) + 1e-6f), fr * 4); }
;     __device__ __forceinline__ void operator()(const f32x4 (&acc)[2][2][4][2], const Unit& u, int wr, int wc, int fr, int fq) const {
;         const int row0 = u.pm * BM + wr * 64 + fr; const int col0 = u.pn * BM + wc * 32 + 8 * fq;
;         float rsa[2][4];
; #pragma unroll
;         for (int ai = 0; ai < 2; ++ai)
; #pragma unroll
;             for (int m = 0; m < 4; ++m) rsa[ai][m] = 1.0f;
;         if (ss) tile_rstd(rsa, ss, u.pm * BM, wr, fr, fq);
	v_pk_add_f32 v[162:163], v[162:163], v[164:165]
	v_pk_add_f32 v[154:155], v[154:155], v[156:157]
	v_mov_b32_e32 v156, v150
	v_mov_b32_e32 v157, v146
	v_mov_b32_e32 v146, v151
	v_mov_b32_e32 v150, v152
	v_mov_b32_e32 v151, v148
	v_mov_b32_e32 v148, v153
	v_pk_add_f32 v[146:147], v[156:157], v[146:147]
	v_pk_add_f32 v[148:149], v[150:151], v[148:149]
	ds_bpermute_b32 v165, v209, v163
	v_pk_add_f32 v[146:147], v[146:147], v[148:149]
	v_mov_b32_e32 v149, v154
	v_mov_b32_e32 v148, v146
	v_mov_b32_e32 v154, v147
	ds_bpermute_b32 v164, v209, v162
	v_pk_add_f32 v[146:147], v[148:149], v[154:155]
	ds_bpermute_b32 v149, v210, v147
	ds_bpermute_b32 v148, v210, v146
	v_mov_b32_e32 v150, v142
	v_mov_b32_e32 v151, v138
	v_mov_b32_e32 v138, v143
	v_mov_b32_e32 v142, v144
	v_mov_b32_e32 v143, v140
	v_mov_b32_e32 v140, v145
	v_pk_add_f32 v[138:139], v[150:151], v[138:139]
	v_pk_add_f32 v[140:141], v[142:143], v[140:141]
	s_waitcnt lgkmcnt(2)
	v_pk_add_f32 v[162:163], v[162:163], v[164:165]
	v_pk_add_f32 v[138:139], v[138:139], v[140:141]
	v_mov_b32_e32 v140, v134
	v_mov_b32_e32 v141, v130
	v_mov_b32_e32 v130, v135
	v_mov_b32_e32 v134, v136
	v_mov_b32_e32 v135, v132
	v_mov_b32_e32 v132, v137
	v_pk_add_f32 v[130:131], v[140:141], v[130:131]
	v_pk_add_f32 v[132:133], v[134:135], v[132:133]
	v_pk_fma_f32 v[162:163], v[162:163], s[18:19], v[202:203] op_sel_hi:[1,0,0]
	v_pk_add_f32 v[130:131], v[130:131], v[132:133]
	s_waitcnt lgkmcnt(0)
	v_pk_add_f32 v[146:147], v[146:147], v[148:149]
	v_mov_b32_e32 v132, v130
	v_mov_b32_e32 v133, v138
	v_mov_b32_e32 v138, v131
	v_mul_f32_e32 v164, 0x4b800000, v163
	v_cmp_gt_f32_e64 s[40:41], s12, v163
	ds_bpermute_b32 v149, v209, v147
	ds_bpermute_b32 v148, v209, v146
	v_pk_add_f32 v[130:131], v[132:133], v[138:139]
	v_cndmask_b32_e64 v163, v163, v164, s[40:41]
	ds_bpermute_b32 v133, v210, v131
	ds_bpermute_b32 v132, v210, v130
	v_rsq_f32_e32 v163, v163
	s_waitcnt lgkmcnt(2)
	v_pk_add_f32 v[146:147], v[146:147], v[148:149]
	v_mul_f32_e32 v211, 0x45800000, v190
	v_pk_fma_f32 v[146:147], v[146:147], s[18:19], v[202:203] op_sel_hi:[1,0,0]
	v_mul_f32_e32 v164, 0x45800000, v163
	s_waitcnt lgkmcnt(0)
	v_pk_add_f32 v[130:131], v[130:131], v[132:133]
	v_cndmask_b32_e64 v163, v163, v164, s[40:41]
	v_mul_f32_e32 v148, 0x4b800000, v147
	v_cmp_gt_f32_e64 s[40:41], s12, v147
	ds_bpermute_b32 v133, v209, v131
	ds_bpermute_b32 v132, v209, v130
	v_cndmask_b32_e32 v190, v190, v211, vcc
	v_cmp_gt_f32_e32 vcc, s12, v162
	ds_bpermute_b32 v164, v208, v163
	v_mul_f32_e32 v163, 0x4b800000, v162
	v_cndmask_b32_e64 v147, v147, v148, s[40:41]
	v_cndmask_b32_e32 v162, v162, v163, vcc
	v_rsq_f32_e32 v147, v147
	v_rsq_f32_e32 v162, v162
	s_waitcnt lgkmcnt(1)
	v_pk_add_f32 v[130:131], v[130:131], v[132:133]
	ds_bpermute_b32 v190, v208, v190
	v_mul_f32_e32 v148, 0x45800000, v147
	v_pk_fma_f32 v[130:131], v[130:131], s[18:19], v[202:203] op_sel_hi:[1,0,0]
	v_mul_f32_e32 v163, 0x45800000, v162
	v_cndmask_b32_e64 v147, v147, v148, s[40:41]
	v_mul_f32_e32 v132, 0x4b800000, v131
	v_cmp_gt_f32_e64 s[40:41], s12, v131
	v_cndmask_b32_e32 v162, v162, v163, vcc
	v_cmp_gt_f32_e32 vcc, s12, v146
	ds_bpermute_b32 v148, v208, v147
	v_mul_f32_e32 v147, 0x4b800000, v146
	v_cndmask_b32_e64 v131, v131, v132, s[40:41]
	v_cndmask_b32_e32 v146, v146, v147, vcc
	v_rsq_f32_e32 v131, v131
	v_rsq_f32_e32 v146, v146
	ds_bpermute_b32 v162, v208, v162
	v_mul_f32_e32 v132, 0x45800000, v131
	v_mul_f32_e32 v147, 0x45800000, v146
	v_cndmask_b32_e64 v131, v131, v132, s[40:41]
	v_cndmask_b32_e32 v146, v146, v147, vcc
	v_cmp_gt_f32_e32 vcc, s12, v130
	ds_bpermute_b32 v132, v208, v131
	v_mul_f32_e32 v131, 0x4b800000, v130
	v_cndmask_b32_e32 v130, v130, v131, vcc
	v_rsq_f32_e32 v130, v130
	ds_bpermute_b32 v146, v208, v146
	v_mul_f32_e32 v131, 0x45800000, v130
	v_cndmask_b32_e32 v130, v130, v131, vcc
	ds_bpermute_b32 v130, v208, v130
	s_waitcnt lgkmcnt(0)
	v_lshrrev_b32_e32 v133, 6, v216
	v_and_b32_e32 v131, 15, v216
	v_lshlrev_b32_e32 v133, 9, v133
	v_lshl_add_u32 v133, v131, 5, v133
	v_add_u32_e32 v133, 0x21000, v133
	ds_write_b32 v133, v132
	ds_write_b32 v133, v130 offset:4
	ds_write_b32 v133, v148 offset:8
	ds_write_b32 v133, v146 offset:12
	ds_write_b32 v133, v164 offset:16
	ds_write_b32 v133, v162 offset:20
	ds_write_b32 v133, v192 offset:24
	ds_write_b32 v133, v190 offset:28
	v_lshrrev_b32_e32 v131, 6, v216
	v_lshlrev_b32_e32 v131, 2, v131
	v_add_u32_e32 v131, 0x22000, v131
	v_mov_b32_e32 v133, s52
	v_add_u32_e32 v133, 1, v133
	ds_write_b32 v131, v133
	s_branch .LBB0_516
.Lst_hit:
	v_lshrrev_b32_e32 v133, 6, v216
	v_and_b32_e32 v131, 15, v216
	v_lshlrev_b32_e32 v133, 9, v133
	v_lshl_add_u32 v133, v131, 5, v133
	v_add_u32_e32 v133, 0x21000, v133
	ds_read_b32 v132, v133
	ds_read_b32 v130, v133 offset:4
	ds_read_b32 v148, v133 offset:8
	ds_read_b32 v146, v133 offset:12
	ds_read_b32 v164, v133 offset:16
	ds_read_b32 v162, v133 offset:20
	ds_read_b32 v192, v133 offset:24
	ds_read_b32 v190, v133 offset:28
	s_waitcnt lgkmcnt(0)
	s_branch .LBB0_516
